# attention: next work-unit index prefetched during the current unit; MoBA block-selection loads issued 16 at a time behind counted waits
# baseline (speedup 1.0000x reference)
; #define LAS __attribute__((address_space(3)))
; DI int tid_opaque() { int t = threadIdx.x; asm volatile("" : "+v"(t)); return t; }
; DI void attn_phase(unsigned char* ws, LAS unsigned char* lds, unsigned* ctr, bool never) {
;     const int tid = tid_opaque();
;     for (;;) {
;         __syncthreads();
;         if (tid == 0) *(LAS int*)(lds + AT_MISC) = (int)atomicAdd(ctr, 1u);
;         __syncthreads();
;         const int u = *(LAS int*)(lds + AT_MISC);
.LBB0_92:
	s_cmp_eq_u32 s41, 3
	s_mov_b64 s[16:17], -1
	s_cbranch_scc0 .LBB0_225
	s_load_dwordx2 s[14:15], s[0:1], 0xa0
	s_ashr_i32 s73, s72, 31
	s_lshl_b64 s[16:17], s[72:73], 2
	v_mov_b32_e32 v0, v210
	s_waitcnt lgkmcnt(0)
	s_add_u32 s16, s14, s16
	s_addc_u32 s17, s15, s17
	s_add_u32 s18, s14, 0xba00000
	s_addc_u32 s19, s15, 0
	s_add_u32 s20, s14, 0x11a00000
	s_addc_u32 s21, s15, 0
	s_add_u32 s22, s14, 0x17a00000
	s_addc_u32 s23, s15, 0
	s_add_u32 s24, s14, 0x1aa00000
	s_addc_u32 s25, s15, 0
	s_add_u32 s26, s14, 0xb800000
	s_addc_u32 s27, s15, 0
	s_add_u32 s28, s14, 0x7800000
	s_addc_u32 s29, s15, 0
	s_add_u32 s9, s14, 0x300000
	v_cmp_eq_u32_e64 s[42:43], 0, v0
	s_addc_u32 s13, s15, 0
	s_and_saveexec_b64 s[38:39], s[42:43]
	s_cbranch_execz .Latt_pf0
	v_mov_b32_e32 v229, 1
	global_atomic_add v228, v1, v229, s[16:17] sc0
.Latt_pf0:
	s_or_b64 exec, exec, s[38:39]
	s_branch .LBB0_97

; #define LAS __attribute__((address_space(3)))
; DI void attn_phase(unsigned char* ws, LAS unsigned char* lds, unsigned* ctr, bool never) {
;     ...
;     for (;;) {
;         __syncthreads();
;         if (tid == 0) *(LAS int*)(lds + AT_MISC) = (int)atomicAdd(ctr, 1u);
;         __syncthreads();
;         const int u = *(LAS int*)(lds + AT_MISC);
;         if (u >= 3072) break;
.LBB0_97:
	s_barrier
	s_and_saveexec_b64 s[38:39], s[42:43]
	s_cbranch_execz .LBB0_101
	s_waitcnt vmcnt(0)
	v_mov_b32_e32 v2, s93
	s_nop 0
	ds_write_b32 v2, v228
	global_atomic_add v228, v1, v229, s[16:17] sc0

; template <int MODE>
; DI void attn_unit(unsigned char* ws, int b, int h, int qb, LAS unsigned char* lds, bool do_store = true) {
;     ...
;             for (int n = 0; n < qb; ++n) { float d = 0.f;
; #pragma unroll
;                 for (int e = 0; e < 64; ++e) d += qv[e] * km[n * 64 + e];
;                 if (d > v0) { v2 = v1; i2 = i1; v1 = v0; i1 = i0; v0 = d; i0 = n; }
;                 else if (d > v1) { v2 = v1; i2 = i1; v1 = d; i1 = n; }
;                 else if (d > v2) { v2 = d; i2 = n; } }
.LBB0_131:
	global_load_dwordx4 v[180:183], v1, s[44:45] offset:48
	global_load_dwordx4 v[184:187], v1, s[44:45] offset:32
	global_load_dwordx4 v[188:191], v1, s[44:45] offset:16
	global_load_dwordx4 v[192:195], v1, s[44:45]
	global_load_dwordx4 v[196:199], v1, s[44:45] offset:112
	global_load_dwordx4 v[200:203], v1, s[44:45] offset:96
	global_load_dwordx4 v[204:207], v1, s[44:45] offset:80
	global_load_dwordx4 v[236:239], v1, s[44:45] offset:64
	global_load_dwordx4 v[240:243], v1, s[44:45] offset:176
	global_load_dwordx4 v[244:247], v1, s[44:45] offset:160
	global_load_dwordx4 v[248:251], v1, s[44:45] offset:144
	global_load_dwordx4 v[224:227], v1, s[44:45] offset:128
	global_load_dwordx4 v[10:13], v1, s[44:45] offset:192
	global_load_dwordx4 v[2:5], v1, s[44:45] offset:240
	global_load_dwordx4 v[6:9], v1, s[44:45] offset:224
	global_load_dwordx4 v[104:107], v1, s[44:45] offset:208
	s_waitcnt vmcnt(12)
	v_fma_f32 v108, v192, v15, 0
	v_fmac_f32_e32 v108, v193, v31
	v_fmac_f32_e32 v108, v194, v32
	v_fmac_f32_e32 v108, v195, v33
	v_fmac_f32_e32 v108, v188, v34
	v_fmac_f32_e32 v108, v189, v35
	v_fmac_f32_e32 v108, v190, v36
	v_fmac_f32_e32 v108, v191, v37
	v_fmac_f32_e32 v108, v184, v38
	v_fmac_f32_e32 v108, v185, v39
	v_fmac_f32_e32 v108, v186, v40
	v_fmac_f32_e32 v108, v187, v41
	v_fmac_f32_e32 v108, v180, v42
	v_fmac_f32_e32 v108, v181, v43
	v_fmac_f32_e32 v108, v182, v44
	v_fmac_f32_e32 v108, v183, v45
	s_waitcnt vmcnt(8)
	v_fmac_f32_e32 v108, v236, v46
	v_fmac_f32_e32 v108, v237, v47
	v_fmac_f32_e32 v108, v238, v48
	v_fmac_f32_e32 v108, v239, v49
	v_fmac_f32_e32 v108, v204, v50
	v_fmac_f32_e32 v108, v205, v51
	v_fmac_f32_e32 v108, v206, v52
	v_fmac_f32_e32 v108, v207, v53
	v_fmac_f32_e32 v108, v200, v54
	v_fmac_f32_e32 v108, v201, v55
	v_fmac_f32_e32 v108, v202, v56
	v_fmac_f32_e32 v108, v203, v57
	v_fmac_f32_e32 v108, v196, v58
	v_fmac_f32_e32 v108, v197, v59
	v_fmac_f32_e32 v108, v198, v60
	v_fmac_f32_e32 v108, v199, v61
	s_waitcnt vmcnt(4)
	v_fmac_f32_e32 v108, v224, v62
	v_fmac_f32_e32 v108, v225, v63
	v_fmac_f32_e32 v108, v226, v64
	v_fmac_f32_e32 v108, v227, v65
	v_fmac_f32_e32 v108, v248, v66
	v_fmac_f32_e32 v108, v249, v67
	v_fmac_f32_e32 v108, v250, v68
	v_fmac_f32_e32 v108, v251, v69
	v_fmac_f32_e32 v108, v244, v70
	v_fmac_f32_e32 v108, v245, v71
	v_fmac_f32_e32 v108, v246, v72
	v_fmac_f32_e32 v108, v247, v73
	v_fmac_f32_e32 v108, v240, v74
	v_fmac_f32_e32 v108, v241, v75
	v_fmac_f32_e32 v108, v242, v76
	v_fmac_f32_e32 v108, v243, v77
	s_waitcnt vmcnt(3)
	v_fmac_f32_e32 v108, v10, v78
	v_fmac_f32_e32 v108, v11, v79
	v_fmac_f32_e32 v108, v12, v80
	v_fmac_f32_e32 v108, v13, v81
	s_waitcnt vmcnt(0)
	v_pk_mul_f32 v[10:11], v[104:105], v[16:17]
	v_pk_mul_f32 v[6:7], v[6:7], v[20:21]
	v_add_f32_e32 v10, v108, v10
	v_add_f32_e32 v12, v10, v11
	v_pk_mul_f32 v[10:11], v[106:107], v[18:19]
	v_pk_mul_f32 v[2:3], v[2:3], v[24:25]
	v_add_f32_e32 v10, v12, v10
	v_add_f32_e32 v10, v10, v11
	v_add_f32_e32 v6, v10, v6
	v_add_f32_e32 v10, v6, v7
	v_pk_mul_f32 v[6:7], v[8:9], v[22:23]
	s_nop 0
	v_add_f32_e32 v6, v10, v6
	v_add_f32_e32 v6, v6, v7
	v_add_f32_e32 v2, v6, v2
	v_add_f32_e32 v6, v2, v3
	v_pk_mul_f32 v[2:3], v[4:5], v[26:27]
	v_mov_b32_e32 v4, s55
	v_add_f32_e32 v2, v6, v2
	v_add_f32_e32 v2, v2, v3
	v_cmp_ngt_f32_e32 vcc, v2, v100
	v_mov_b32_e32 v3, v102
	v_mov_b32_e32 v5, v100
	s_and_saveexec_b64 s[46:47], vcc
	s_cbranch_execz .LBB0_137
	v_cmp_ngt_f32_e32 vcc, v2, v101
	v_mov_b32_e32 v3, s55
	s_and_saveexec_b64 s[48:49], vcc
	s_cbranch_execz .LBB0_136
	v_cmp_gt_f32_e32 vcc, v2, v103
	s_and_saveexec_b64 s[50:51], vcc
	v_mov_b32_e32 v98, s55
	v_mov_b32_e32 v103, v2
	s_or_b64 exec, exec, s[50:51]
	v_mov_b32_e32 v2, v101
	v_mov_b32_e32 v101, v103
	v_mov_b32_e32 v3, v99
	v_mov_b32_e32 v99, v98
